# v30 + nt policy on final output stores and HM stores
# speedup vs baseline: 1.0290x; 1.0036x over previous
; #define PG8_LAS __attribute__((address_space(3)))
;     __device__ __forceinline__ void fused(f32x4 (&acc)[2][2][4][2], const Unit& u, int wr, int wc, int fr, int fq, PG8_LAS unsigned char* lds, int wid, int lane) const {
;     ...
;         { constexpr int TROW = 1040, TSZ = 64 * TROW; const f32x4 gcol = *(const f32x4*)(gain + (size_t)u.pn * BM + 4 * lane);
; #pragma unroll
;           for (int p = 0; p < 4; ++p) { const int ai = p >> 1, wrp = p & 1; PG8_LAS unsigned char* T = lds + 8192 + (p & 1) * TSZ;
;               if (wr == wrp) {
; #pragma unroll
;                   for (int bj = 0; bj < 2; ++bj)
; #pragma unroll
;                       for (int m = 0; m < 4; ++m)
; #pragma unroll
;                           for (int n = 0; n < 2; ++n) *(PG8_LAS f32x4*)(T + (m * 16 + fr) * TROW + (bj * HALF + wc * 32 + 8 * fq + 4 * n) * 4) = acc[ai][bj][m][n];
;               }
;               asm volatile("s_waitcnt lgkmcnt(0)" ::: "memory"); __builtin_amdgcn_s_barrier(); asm volatile("" ::: "memory");
; #pragma unroll
;               for (int r = 0; r < 8; ++r) { const int rl = p * 64 + 8 * wid + r; const f32x4 t = *(const PG8_LAS f32x4*)(T + (8 * wid + r) * TROW + lane * 16);
;                   *(f32x4*)(out + (size_t)(u.pm * BM + rl) * ldc + (size_t)u.pn * BM + 4 * lane) = t * tbl[rl] * gcol; } } }
;         asm volatile("s_waitcnt lgkmcnt(0)" ::: "memory"); __builtin_amdgcn_s_barrier(); asm volatile("" ::: "memory");
.LBB0_336:
	s_mul_i32 s13, s20, 0x2080
	v_add_u32_e32 v147, 0, v2
	s_lshl_b32 s2, s20, 5
	s_lshl_b32 s16, s20, 3
	s_waitcnt lgkmcnt(0)
	s_barrier
	v_add_u32_e32 v146, s13, v147
	s_add_i32 s12, s2, 0
	ds_read_b128 v[148:151], v146 offset:8192
	v_mov_b32_e32 v140, s12
	s_add_i32 s6, s38, s16
	ds_read_b128 v[152:155], v140 offset:4096
	ds_read_b128 v[140:143], v140 offset:4112
	s_ashr_i32 s7, s6, 31
	s_lshl_b64 s[2:3], s[6:7], 13
	s_add_u32 s2, s68, s2
	s_addc_u32 s3, s69, s3
	v_lshlrev_b32_e32 v0, 2, v0
	s_waitcnt lgkmcnt(1)
	v_pk_mul_f32 v[150:151], v[150:151], v[152:153] op_sel_hi:[1,0]
	v_pk_mul_f32 v[148:149], v[148:149], v[152:153] op_sel_hi:[1,0]
	s_add_u32 s2, s2, s0
	s_waitcnt vmcnt(0)
	v_pk_mul_f32 v[150:151], v[138:139], v[150:151]
	v_pk_mul_f32 v[148:149], v[136:137], v[148:149]
	s_addc_u32 s3, s3, s1
	v_lshlrev_b32_e32 v0, 2, v0
	global_store_dwordx4 v0, v[148:151], s[2:3] nt
	s_or_b32 s2, s16, 1
	s_mul_i32 s7, s2, 0x410
	v_add_u32_e32 v145, s7, v147
	ds_read_b128 v[148:151], v145 offset:8192
	s_add_i32 s2, s38, s2
	s_ashr_i32 s3, s2, 31
	s_lshl_b64 s[2:3], s[2:3], 13
	s_add_u32 s2, s68, s2
	s_addc_u32 s3, s69, s3
	s_waitcnt lgkmcnt(0)
	v_pk_mul_f32 v[150:151], v[150:151], v[152:153] op_sel:[0,1]
	v_pk_mul_f32 v[148:149], v[148:149], v[152:153] op_sel:[0,1]
	s_add_u32 s2, s2, s0
	v_pk_mul_f32 v[150:151], v[138:139], v[150:151]
	v_pk_mul_f32 v[148:149], v[136:137], v[148:149]
	s_addc_u32 s3, s3, s1
	global_store_dwordx4 v0, v[148:151], s[2:3] nt
	s_add_i32 s2, s7, 0x410
	v_mov_b32_e32 v152, v155
	v_add_u32_e32 v148, s2, v147
	ds_read_b128 v[148:151], v148 offset:8192
	s_add_i32 s2, s6, 2
	s_ashr_i32 s3, s2, 31
	s_lshl_b64 s[2:3], s[2:3], 13
	s_add_u32 s2, s68, s2
	s_addc_u32 s3, s69, s3
	s_waitcnt lgkmcnt(0)
	v_pk_mul_f32 v[150:151], v[150:151], v[154:155] op_sel_hi:[1,0]
	v_pk_mul_f32 v[148:149], v[148:149], v[154:155] op_sel_hi:[1,0]
	s_add_u32 s2, s2, s0
	v_pk_mul_f32 v[150:151], v[138:139], v[150:151]
	v_pk_mul_f32 v[148:149], v[136:137], v[148:149]
	s_addc_u32 s3, s3, s1
	global_store_dwordx4 v0, v[148:151], s[2:3] nt
	s_add_i32 s2, s7, 0x820
	s_nop 0
	v_add_u32_e32 v148, s2, v147
	ds_read_b128 v[148:151], v148 offset:8192
	s_add_i32 s2, s6, 3
	s_ashr_i32 s3, s2, 31
	s_lshl_b64 s[2:3], s[2:3], 13
	s_add_u32 s2, s68, s2
	s_addc_u32 s3, s69, s3
	s_waitcnt lgkmcnt(0)
	v_pk_mul_f32 v[150:151], v[150:151], v[152:153] op_sel_hi:[1,0]
	v_pk_mul_f32 v[148:149], v[148:149], v[152:153] op_sel_hi:[1,0]
	s_add_u32 s2, s2, s0
	v_pk_mul_f32 v[150:151], v[138:139], v[150:151]
	v_pk_mul_f32 v[148:149], v[136:137], v[148:149]
	s_addc_u32 s3, s3, s1
	global_store_dwordx4 v0, v[148:151], s[2:3] nt
	s_add_i32 s2, s7, 0xc30
	s_nop 0
	v_add_u32_e32 v148, s2, v147
	ds_read_b128 v[148:151], v148 offset:8192
	s_add_i32 s2, s6, 4
	s_ashr_i32 s3, s2, 31
	s_lshl_b64 s[2:3], s[2:3], 13
	s_add_u32 s2, s68, s2
	s_addc_u32 s3, s69, s3
	s_waitcnt lgkmcnt(0)
	v_pk_mul_f32 v[150:151], v[150:151], v[140:141] op_sel_hi:[1,0]
	v_pk_mul_f32 v[148:149], v[148:149], v[140:141] op_sel_hi:[1,0]
	s_add_u32 s2, s2, s0
	v_pk_mul_f32 v[150:151], v[138:139], v[150:151]
	v_pk_mul_f32 v[148:149], v[136:137], v[148:149]
	s_addc_u32 s3, s3, s1
	global_store_dwordx4 v0, v[148:151], s[2:3] nt
	s_add_i32 s2, s7, 0x1040
	s_nop 0
	v_add_u32_e32 v148, s2, v147
	ds_read_b128 v[148:151], v148 offset:8192
	s_add_i32 s2, s6, 5
	s_ashr_i32 s3, s2, 31
	s_lshl_b64 s[2:3], s[2:3], 13
	s_add_u32 s2, s68, s2
	s_addc_u32 s3, s69, s3
	s_waitcnt lgkmcnt(0)
	v_pk_mul_f32 v[150:151], v[150:151], v[140:141] op_sel:[0,1]
	v_pk_mul_f32 v[140:141], v[148:149], v[140:141] op_sel:[0,1]
	s_add_u32 s2, s2, s0
	v_pk_mul_f32 v[150:151], v[138:139], v[150:151]
	v_pk_mul_f32 v[148:149], v[136:137], v[140:141]
	s_addc_u32 s3, s3, s1
	global_store_dwordx4 v0, v[148:151], s[2:3] nt
	s_add_i32 s2, s7, 0x1450
	v_add_u32_e32 v140, s2, v147
	ds_read_b128 v[148:151], v140 offset:8192
	s_add_i32 s2, s6, 6
	s_ashr_i32 s3, s2, 31
	s_lshl_b64 s[2:3], s[2:3], 13
	s_add_u32 s2, s68, s2
	s_addc_u32 s3, s69, s3
	s_waitcnt lgkmcnt(0)
	v_pk_mul_f32 v[140:141], v[150:151], v[142:143] op_sel_hi:[1,0]
	v_pk_mul_f32 v[148:149], v[148:149], v[142:143] op_sel_hi:[1,0]
	s_add_u32 s2, s2, s0
	v_pk_mul_f32 v[150:151], v[138:139], v[140:141]
	v_pk_mul_f32 v[148:149], v[136:137], v[148:149]
	s_addc_u32 s3, s3, s1
	global_store_dwordx4 v0, v[148:151], s[2:3] nt
	s_add_i32 s2, s7, 0x1860
	v_add_u32_e32 v140, s2, v147
	ds_read_b128 v[148:151], v140 offset:8192
	s_add_i32 s2, s6, 7
	s_ashr_i32 s3, s2, 31
	s_lshl_b64 s[2:3], s[2:3], 13
	s_add_u32 s2, s68, s2
	v_mov_b32_e32 v140, v143
	s_addc_u32 s3, s69, s3
	s_waitcnt lgkmcnt(0)
	v_pk_mul_f32 v[142:143], v[150:151], v[140:141] op_sel_hi:[1,0]
	v_pk_mul_f32 v[140:141], v[148:149], v[140:141] op_sel_hi:[1,0]
	s_add_u32 s2, s2, s0
	v_pk_mul_f32 v[142:143], v[138:139], v[142:143]
	v_pk_mul_f32 v[140:141], v[136:137], v[140:141]
	s_addc_u32 s3, s3, s1
	global_store_dwordx4 v0, v[140:143], s[2:3] nt
	s_andn2_b64 vcc, exec, s[10:11]
	s_nop 0
	v_cndmask_b32_e64 v140, 0, 1, s[10:11]
	v_cmp_ne_u32_e64 s[2:3], 1, v140
	s_cbranch_vccnz .LBB0_338
	v_readlane_b32 s10, v252, 22
	s_nop 1
	v_add3_u32 v140, s10, v3, v144
	ds_write_b128 v140, v[8:11]
	ds_write_b128 v140, v[12:15] offset:16
	ds_write_b128 v140, v[48:51] offset:16640
	ds_write_b128 v140, v[52:55] offset:16656
	ds_write_b128 v140, v[96:99] offset:33280
	ds_write_b128 v140, v[100:103] offset:33296
	ds_write_b128 v140, v[120:123] offset:49920
	ds_write_b128 v140, v[124:127] offset:49936
	ds_write_b128 v140, v[24:27] offset:512
	ds_write_b128 v140, v[28:31] offset:528
	ds_write_b128 v140, v[72:75] offset:17152
	ds_write_b128 v140, v[76:79] offset:17168
	ds_write_b128 v140, v[112:115] offset:33792
	ds_write_b128 v140, v[116:119] offset:33808
	ds_write_b128 v140, v[128:131] offset:50432
	ds_write_b128 v140, v[132:135] offset:50448
; #define PG8_LAS __attribute__((address_space(3)))
;     __device__ __forceinline__ void fused(f32x4 (&acc)[2][2][4][2], const Unit& u, int wr, int wc, int fr, int fq, PG8_LAS unsigned char* lds, int wid, int lane) const {
;     ...
;         { constexpr int TROW = 1040, TSZ = 64 * TROW; const f32x4 gcol = *(const f32x4*)(gain + (size_t)u.pn * BM + 4 * lane);
; #pragma unroll
;           for (int p = 0; p < 4; ++p) { const int ai = p >> 1, wrp = p & 1; PG8_LAS unsigned char* T = lds + 8192 + (p & 1) * TSZ;
;               if (wr == wrp) {
; #pragma unroll
;                   for (int bj = 0; bj < 2; ++bj)
; #pragma unroll
;                       for (int m = 0; m < 4; ++m)
; #pragma unroll
;                           for (int n = 0; n < 2; ++n) *(PG8_LAS f32x4*)(T + (m * 16 + fr) * TROW + (bj * HALF + wc * 32 + 8 * fq + 4 * n) * 4) = acc[ai][bj][m][n];
;               }
;               asm volatile("s_waitcnt lgkmcnt(0)" ::: "memory"); __builtin_amdgcn_s_barrier(); asm volatile("" ::: "memory");
; #pragma unroll
;               for (int r = 0; r < 8; ++r) { const int rl = p * 64 + 8 * wid + r; const f32x4 t = *(const PG8_LAS f32x4*)(T + (8 * wid + r) * TROW + lane * 16);
;                   *(f32x4*)(out + (size_t)(u.pm * BM + rl) * ldc + (size_t)u.pn * BM + 4 * lane) = t * tbl[rl] * gcol; } } }
;         asm volatile("s_waitcnt lgkmcnt(0)" ::: "memory"); __builtin_amdgcn_s_barrier(); asm volatile("" ::: "memory");
.LBB0_338:
	v_readlane_b32 s10, v252, 22
	s_waitcnt lgkmcnt(0)
	s_barrier
	v_mov_b32_e32 v8, s12
	v_add_u32_e32 v2, s10, v2
	v_add_u32_e32 v24, s13, v2
	ds_read_b128 v[12:15], v24
	s_add_i32 s10, s6, 64
	ds_read_b128 v[26:29], v8 offset:4352
	ds_read_b128 v[8:11], v8 offset:4368
	s_ashr_i32 s11, s10, 31
	s_lshl_b64 s[10:11], s[10:11], 13
	s_add_u32 s10, s68, s10
	s_addc_u32 s11, s69, s11
	s_waitcnt lgkmcnt(1)
	v_pk_mul_f32 v[14:15], v[14:15], v[26:27] op_sel_hi:[1,0]
	v_pk_mul_f32 v[12:13], v[12:13], v[26:27] op_sel_hi:[1,0]
	s_add_u32 s10, s10, s0
	v_pk_mul_f32 v[14:15], v[138:139], v[14:15]
	v_pk_mul_f32 v[12:13], v[136:137], v[12:13]
	s_addc_u32 s11, s11, s1
	v_add_u32_e32 v2, s7, v2
	global_store_dwordx4 v0, v[12:15], s[10:11] nt
	ds_read_b128 v[12:15], v2
	s_add_i32 s10, s6, 0x41
	s_ashr_i32 s11, s10, 31
	s_lshl_b64 s[10:11], s[10:11], 13
	s_add_u32 s7, s68, s10
	s_addc_u32 s11, s69, s11
	s_waitcnt lgkmcnt(0)
	v_pk_mul_f32 v[14:15], v[14:15], v[26:27] op_sel:[0,1]
	v_pk_mul_f32 v[12:13], v[12:13], v[26:27] op_sel:[0,1]
	s_add_u32 s10, s7, s0
	v_pk_mul_f32 v[14:15], v[138:139], v[14:15]
	v_pk_mul_f32 v[12:13], v[136:137], v[12:13]
	s_addc_u32 s11, s11, s1
	global_store_dwordx4 v0, v[12:15], s[10:11] nt
	ds_read_b128 v[12:15], v2 offset:1040
	s_add_i32 s10, s6, 0x42
	s_ashr_i32 s11, s10, 31
	s_lshl_b64 s[10:11], s[10:11], 13
	s_add_u32 s7, s68, s10
	s_addc_u32 s11, s69, s11
	s_waitcnt lgkmcnt(0)
	v_pk_mul_f32 v[14:15], v[14:15], v[28:29] op_sel_hi:[1,0]
	v_pk_mul_f32 v[12:13], v[12:13], v[28:29] op_sel_hi:[1,0]
	s_add_u32 s10, s7, s0
	v_pk_mul_f32 v[12:13], v[136:137], v[12:13]
	v_pk_mul_f32 v[14:15], v[138:139], v[14:15]
	s_addc_u32 s11, s11, s1
	global_store_dwordx4 v0, v[12:15], s[10:11] nt
	ds_read_b128 v[12:15], v2 offset:2080
	s_add_i32 s10, s6, 0x43
	s_ashr_i32 s11, s10, 31
	s_lshl_b64 s[10:11], s[10:11], 13
	s_add_u32 s7, s68, s10
	v_mov_b32_e32 v26, v29
	s_addc_u32 s11, s69, s11
	s_waitcnt lgkmcnt(0)
	v_pk_mul_f32 v[14:15], v[14:15], v[26:27] op_sel_hi:[1,0]
	v_pk_mul_f32 v[12:13], v[12:13], v[26:27] op_sel_hi:[1,0]
	s_add_u32 s10, s7, s0
	v_pk_mul_f32 v[12:13], v[136:137], v[12:13]
	v_pk_mul_f32 v[14:15], v[138:139], v[14:15]
	s_addc_u32 s11, s11, s1
	global_store_dwordx4 v0, v[12:15], s[10:11] nt
	ds_read_b128 v[12:15], v2 offset:3120
	s_add_i32 s10, s6, 0x44
	s_ashr_i32 s11, s10, 31
	s_lshl_b64 s[10:11], s[10:11], 13
	s_add_u32 s7, s68, s10
	s_addc_u32 s11, s69, s11
	s_waitcnt lgkmcnt(0)
	v_pk_mul_f32 v[14:15], v[14:15], v[8:9] op_sel_hi:[1,0]
	v_pk_mul_f32 v[12:13], v[12:13], v[8:9] op_sel_hi:[1,0]
	s_add_u32 s10, s7, s0
	v_pk_mul_f32 v[14:15], v[138:139], v[14:15]
	v_pk_mul_f32 v[12:13], v[136:137], v[12:13]
	s_addc_u32 s11, s11, s1
	global_store_dwordx4 v0, v[12:15], s[10:11] nt
	ds_read_b128 v[12:15], v2 offset:4160
	s_add_i32 s10, s6, 0x45
	s_ashr_i32 s11, s10, 31
	s_lshl_b64 s[10:11], s[10:11], 13
	s_add_u32 s7, s68, s10
	s_addc_u32 s11, s69, s11
	s_waitcnt lgkmcnt(0)
	v_pk_mul_f32 v[14:15], v[14:15], v[8:9] op_sel:[0,1]
	v_pk_mul_f32 v[8:9], v[12:13], v[8:9] op_sel:[0,1]
	s_add_u32 s10, s7, s0
	v_pk_mul_f32 v[14:15], v[138:139], v[14:15]
	v_pk_mul_f32 v[12:13], v[136:137], v[8:9]
	s_addc_u32 s11, s11, s1
	global_store_dwordx4 v0, v[12:15], s[10:11] nt
	ds_read_b128 v[12:15], v2 offset:5200
	s_add_i32 s10, s6, 0x46
	s_ashr_i32 s11, s10, 31
	s_lshl_b64 s[10:11], s[10:11], 13
	s_add_u32 s7, s68, s10
	s_addc_u32 s11, s69, s11
	s_waitcnt lgkmcnt(0)
	v_pk_mul_f32 v[8:9], v[14:15], v[10:11] op_sel_hi:[1,0]
	v_pk_mul_f32 v[12:13], v[12:13], v[10:11] op_sel_hi:[1,0]
	s_add_u32 s10, s7, s0
	v_pk_mul_f32 v[12:13], v[136:137], v[12:13]
	v_pk_mul_f32 v[14:15], v[138:139], v[8:9]
	s_addc_u32 s11, s11, s1
	global_store_dwordx4 v0, v[12:15], s[10:11] nt
	ds_read_b128 v[12:15], v2 offset:6240
	s_add_i32 s10, s6, 0x47
	s_ashr_i32 s11, s10, 31
	s_lshl_b64 s[10:11], s[10:11], 13
	s_add_u32 s7, s68, s10
	v_mov_b32_e32 v8, v11
	s_addc_u32 s11, s69, s11
	s_waitcnt lgkmcnt(0)
	v_pk_mul_f32 v[10:11], v[14:15], v[8:9] op_sel_hi:[1,0]
	v_pk_mul_f32 v[8:9], v[12:13], v[8:9] op_sel_hi:[1,0]
	s_add_u32 s10, s7, s0
	v_pk_mul_f32 v[8:9], v[136:137], v[8:9]
	v_pk_mul_f32 v[10:11], v[138:139], v[10:11]
	s_addc_u32 s11, s11, s1
	s_and_b64 vcc, exec, s[4:5]
	global_store_dwordx4 v0, v[8:11], s[10:11] nt
	s_cbranch_vccnz .LBB0_340
	s_nop 0
	v_add3_u32 v8, 0, v3, v144
	ds_write_b128 v8, v[16:19] offset:8192
	ds_write_b128 v8, v[20:23] offset:8208
	ds_write_b128 v8, v[56:59] offset:24832
	ds_write_b128 v8, v[60:63] offset:24848
	ds_write_b128 v8, v[104:107] offset:41472
	ds_write_b128 v8, v[108:111] offset:41488
	ds_write_b128 v8, v[68:71] offset:58112
	ds_write_b128 v8, v[64:67] offset:58128
	ds_write_b128 v8, v[40:43] offset:8704
	ds_write_b128 v8, v[44:47] offset:8720
	ds_write_b128 v8, v[88:91] offset:25344
	ds_write_b128 v8, v[92:95] offset:25360
	ds_write_b128 v8, v[84:87] offset:41984
	ds_write_b128 v8, v[80:83] offset:42000
	ds_write_b128 v8, v[36:39] offset:58624
	ds_write_b128 v8, v[32:35] offset:58640
; #define PG8_LAS __attribute__((address_space(3)))
;     __device__ __forceinline__ void fused(f32x4 (&acc)[2][2][4][2], const Unit& u, int wr, int wc, int fr, int fq, PG8_LAS unsigned char* lds, int wid, int lane) const {
;     ...
;         { constexpr int TROW = 1040, TSZ = 64 * TROW; const f32x4 gcol = *(const f32x4*)(gain + (size_t)u.pn * BM + 4 * lane);
; #pragma unroll
;           for (int p = 0; p < 4; ++p) { const int ai = p >> 1, wrp = p & 1; PG8_LAS unsigned char* T = lds + 8192 + (p & 1) * TSZ;
;               if (wr == wrp) {
; #pragma unroll
;                   for (int bj = 0; bj < 2; ++bj)
; #pragma unroll
;                       for (int m = 0; m < 4; ++m)
; #pragma unroll
;                           for (int n = 0; n < 2; ++n) *(PG8_LAS f32x4*)(T + (m * 16 + fr) * TROW + (bj * HALF + wc * 32 + 8 * fq + 4 * n) * 4) = acc[ai][bj][m][n];
;               }
;               asm volatile("s_waitcnt lgkmcnt(0)" ::: "memory"); __builtin_amdgcn_s_barrier(); asm volatile("" ::: "memory");
; #pragma unroll
;               for (int r = 0; r < 8; ++r) { const int rl = p * 64 + 8 * wid + r; const f32x4 t = *(const PG8_LAS f32x4*)(T + (8 * wid + r) * TROW + lane * 16);
;                   *(f32x4*)(out + (size_t)(u.pm * BM + rl) * ldc + (size_t)u.pn * BM + 4 * lane) = t * tbl[rl] * gcol; } } }
;         asm volatile("s_waitcnt lgkmcnt(0)" ::: "memory"); __builtin_amdgcn_s_barrier(); asm volatile("" ::: "memory");
.LBB0_340:
	s_waitcnt lgkmcnt(0)
	s_barrier
	ds_read_b128 v[26:29], v146 offset:8192
	v_mov_b32_e32 v8, s12
	s_add_i32 s4, s6, 0x80
	ds_read_b128 v[12:15], v8 offset:4608
	ds_read_b128 v[8:11], v8 offset:4624
	s_ashr_i32 s5, s4, 31
	s_lshl_b64 s[4:5], s[4:5], 13
	s_add_u32 s4, s68, s4
	s_addc_u32 s5, s69, s5
	s_waitcnt lgkmcnt(1)
	v_pk_mul_f32 v[28:29], v[28:29], v[12:13] op_sel_hi:[1,0]
	v_pk_mul_f32 v[26:27], v[26:27], v[12:13] op_sel_hi:[1,0]
	s_add_u32 s4, s4, s0
	v_pk_mul_f32 v[28:29], v[138:139], v[28:29]
	v_pk_mul_f32 v[26:27], v[136:137], v[26:27]
	s_addc_u32 s5, s5, s1
	global_store_dwordx4 v0, v[26:29], s[4:5] nt
	ds_read_b128 v[26:29], v145 offset:8192
	s_add_i32 s4, s6, 0x81
	s_ashr_i32 s5, s4, 31
	s_lshl_b64 s[4:5], s[4:5], 13
	s_add_u32 s4, s68, s4
	s_addc_u32 s5, s69, s5
	s_waitcnt lgkmcnt(0)
	v_pk_mul_f32 v[28:29], v[28:29], v[12:13] op_sel:[0,1]
	v_pk_mul_f32 v[12:13], v[26:27], v[12:13] op_sel:[0,1]
	s_add_u32 s4, s4, s0
	v_pk_mul_f32 v[28:29], v[138:139], v[28:29]
	v_pk_mul_f32 v[26:27], v[136:137], v[12:13]
	s_addc_u32 s5, s5, s1
	global_store_dwordx4 v0, v[26:29], s[4:5] nt
	ds_read_b128 v[26:29], v145 offset:9232
	s_add_i32 s4, s6, 0x82
	s_ashr_i32 s5, s4, 31
	s_lshl_b64 s[4:5], s[4:5], 13
	s_add_u32 s4, s68, s4
	s_addc_u32 s5, s69, s5
	s_waitcnt lgkmcnt(0)
	v_pk_mul_f32 v[12:13], v[26:27], v[14:15] op_sel_hi:[1,0]
	v_pk_mul_f32 v[26:27], v[28:29], v[14:15] op_sel_hi:[1,0]
	s_add_u32 s4, s4, s0
	v_pk_mul_f32 v[28:29], v[138:139], v[26:27]
	v_pk_mul_f32 v[26:27], v[136:137], v[12:13]
	s_addc_u32 s5, s5, s1
	global_store_dwordx4 v0, v[26:29], s[4:5] nt
	ds_read_b128 v[26:29], v145 offset:10272
	s_add_i32 s4, s6, 0x83
	s_ashr_i32 s5, s4, 31
	s_lshl_b64 s[4:5], s[4:5], 13
	s_add_u32 s4, s68, s4
	v_mov_b32_e32 v12, v15
	s_addc_u32 s5, s69, s5
	s_waitcnt lgkmcnt(0)
	v_pk_mul_f32 v[26:27], v[26:27], v[12:13] op_sel_hi:[1,0]
	v_pk_mul_f32 v[12:13], v[28:29], v[12:13] op_sel_hi:[1,0]
	s_add_u32 s4, s4, s0
	v_pk_mul_f32 v[14:15], v[138:139], v[12:13]
	v_pk_mul_f32 v[12:13], v[136:137], v[26:27]
	s_addc_u32 s5, s5, s1
	global_store_dwordx4 v0, v[12:15], s[4:5] nt
	ds_read_b128 v[12:15], v145 offset:11312
	s_add_i32 s4, s6, 0x84
	s_ashr_i32 s5, s4, 31
	s_lshl_b64 s[4:5], s[4:5], 13
	s_add_u32 s4, s68, s4
	s_addc_u32 s5, s69, s5
	s_waitcnt lgkmcnt(0)
	v_pk_mul_f32 v[14:15], v[14:15], v[8:9] op_sel_hi:[1,0]
	v_pk_mul_f32 v[12:13], v[12:13], v[8:9] op_sel_hi:[1,0]
	s_add_u32 s4, s4, s0
	v_pk_mul_f32 v[14:15], v[138:139], v[14:15]
	v_pk_mul_f32 v[12:13], v[136:137], v[12:13]
	s_addc_u32 s5, s5, s1
	global_store_dwordx4 v0, v[12:15], s[4:5] nt
	ds_read_b128 v[12:15], v145 offset:12352
	s_add_i32 s4, s6, 0x85
	s_ashr_i32 s5, s4, 31
	s_lshl_b64 s[4:5], s[4:5], 13
	s_add_u32 s4, s68, s4
	s_addc_u32 s5, s69, s5
	s_waitcnt lgkmcnt(0)
	v_pk_mul_f32 v[14:15], v[14:15], v[8:9] op_sel:[0,1]
	v_pk_mul_f32 v[8:9], v[12:13], v[8:9] op_sel:[0,1]
	s_add_u32 s4, s4, s0
	v_pk_mul_f32 v[14:15], v[138:139], v[14:15]
	v_pk_mul_f32 v[12:13], v[136:137], v[8:9]
	s_addc_u32 s5, s5, s1
	global_store_dwordx4 v0, v[12:15], s[4:5] nt
	ds_read_b128 v[12:15], v145 offset:13392
	s_add_i32 s4, s6, 0x86
	s_ashr_i32 s5, s4, 31
	s_lshl_b64 s[4:5], s[4:5], 13
	s_add_u32 s4, s68, s4
	s_addc_u32 s5, s69, s5
	s_waitcnt lgkmcnt(0)
	v_pk_mul_f32 v[8:9], v[12:13], v[10:11] op_sel_hi:[1,0]
	v_pk_mul_f32 v[12:13], v[14:15], v[10:11] op_sel_hi:[1,0]
	s_add_u32 s4, s4, s0
	v_pk_mul_f32 v[14:15], v[138:139], v[12:13]
	v_pk_mul_f32 v[12:13], v[136:137], v[8:9]
	s_addc_u32 s5, s5, s1
	global_store_dwordx4 v0, v[12:15], s[4:5] nt
	ds_read_b128 v[12:15], v145 offset:14432
	s_add_i32 s4, s6, 0x87
	s_ashr_i32 s5, s4, 31
	s_lshl_b64 s[4:5], s[4:5], 13
	s_add_u32 s4, s68, s4
	v_mov_b32_e32 v8, v11
	s_addc_u32 s5, s69, s5
	s_waitcnt lgkmcnt(0)
	v_pk_mul_f32 v[12:13], v[12:13], v[8:9] op_sel_hi:[1,0]
	v_pk_mul_f32 v[8:9], v[14:15], v[8:9] op_sel_hi:[1,0]
	s_add_u32 s4, s4, s0
	v_pk_mul_f32 v[10:11], v[138:139], v[8:9]
	v_pk_mul_f32 v[8:9], v[136:137], v[12:13]
	s_addc_u32 s5, s5, s1
	s_and_b64 vcc, exec, s[2:3]
	global_store_dwordx4 v0, v[8:11], s[4:5] nt
	s_cbranch_vccnz .LBB0_342
	v_readlane_b32 s2, v252, 22
	s_nop 1
	v_add3_u32 v3, s2, v3, v144
	ds_write_b128 v3, v[16:19]
	ds_write_b128 v3, v[20:23] offset:16
	ds_write_b128 v3, v[56:59] offset:16640
	ds_write_b128 v3, v[60:63] offset:16656
	ds_write_b128 v3, v[104:107] offset:33280
	ds_write_b128 v3, v[108:111] offset:33296
	ds_write_b128 v3, v[68:71] offset:49920
	ds_write_b128 v3, v[64:67] offset:49936
	ds_write_b128 v3, v[40:43] offset:512
	ds_write_b128 v3, v[44:47] offset:528
	ds_write_b128 v3, v[88:91] offset:17152
	ds_write_b128 v3, v[92:95] offset:17168
	ds_write_b128 v3, v[84:87] offset:33792
	ds_write_b128 v3, v[80:83] offset:33808
	ds_write_b128 v3, v[36:39] offset:50432
	ds_write_b128 v3, v[32:35] offset:50448
; #define PG8_LAS __attribute__((address_space(3)))
;     __device__ __forceinline__ void fused(f32x4 (&acc)[2][2][4][2], const Unit& u, int wr, int wc, int fr, int fq, PG8_LAS unsigned char* lds, int wid, int lane) const {
;     ...
;         { constexpr int TROW = 1040, TSZ = 64 * TROW; const f32x4 gcol = *(const f32x4*)(gain + (size_t)u.pn * BM + 4 * lane);
; #pragma unroll
;           for (int p = 0; p < 4; ++p) { const int ai = p >> 1, wrp = p & 1; PG8_LAS unsigned char* T = lds + 8192 + (p & 1) * TSZ;
;               if (wr == wrp) {
; #pragma unroll
;                   for (int bj = 0; bj < 2; ++bj)
; #pragma unroll
;                       for (int m = 0; m < 4; ++m)
; #pragma unroll
;                           for (int n = 0; n < 2; ++n) *(PG8_LAS f32x4*)(T + (m * 16 + fr) * TROW + (bj * HALF + wc * 32 + 8 * fq + 4 * n) * 4) = acc[ai][bj][m][n];
;               }
;               asm volatile("s_waitcnt lgkmcnt(0)" ::: "memory"); __builtin_amdgcn_s_barrier(); asm volatile("" ::: "memory");
; #pragma unroll
;               for (int r = 0; r < 8; ++r) { const int rl = p * 64 + 8 * wid + r; const f32x4 t = *(const PG8_LAS f32x4*)(T + (8 * wid + r) * TROW + lane * 16);
;                   *(f32x4*)(out + (size_t)(u.pm * BM + rl) * ldc + (size_t)u.pn * BM + 4 * lane) = t * tbl[rl] * gcol; } } }
;         asm volatile("s_waitcnt lgkmcnt(0)" ::: "memory"); __builtin_amdgcn_s_barrier(); asm volatile("" ::: "memory");
.LBB0_342:
	s_waitcnt lgkmcnt(0)
	s_barrier
	ds_read_b128 v[16:19], v24
	v_mov_b32_e32 v3, s12
	s_add_i32 s2, s6, 0xc0
	ds_read_b128 v[12:15], v3 offset:4864
	ds_read_b128 v[8:11], v3 offset:4880
	s_ashr_i32 s3, s2, 31
	s_lshl_b64 s[2:3], s[2:3], 13
	s_add_u32 s2, s68, s2
	s_addc_u32 s3, s69, s3
	s_waitcnt lgkmcnt(1)
	v_pk_mul_f32 v[18:19], v[18:19], v[12:13] op_sel_hi:[1,0]
	v_pk_mul_f32 v[16:17], v[16:17], v[12:13] op_sel_hi:[1,0]
	s_add_u32 s2, s2, s0
	v_pk_mul_f32 v[18:19], v[138:139], v[18:19]
	v_pk_mul_f32 v[16:17], v[136:137], v[16:17]
	s_addc_u32 s3, s3, s1
	global_store_dwordx4 v0, v[16:19], s[2:3] nt
	ds_read_b128 v[16:19], v2
	s_add_i32 s2, s6, 0xc1
	s_ashr_i32 s3, s2, 31
	s_lshl_b64 s[2:3], s[2:3], 13
	s_add_u32 s2, s68, s2
	s_addc_u32 s3, s69, s3
	s_waitcnt lgkmcnt(0)
	v_pk_mul_f32 v[18:19], v[18:19], v[12:13] op_sel:[0,1]
	v_pk_mul_f32 v[12:13], v[16:17], v[12:13] op_sel:[0,1]
	s_add_u32 s2, s2, s0
	v_pk_mul_f32 v[18:19], v[138:139], v[18:19]
	v_pk_mul_f32 v[16:17], v[136:137], v[12:13]
	s_addc_u32 s3, s3, s1
	global_store_dwordx4 v0, v[16:19], s[2:3] nt
	ds_read_b128 v[16:19], v2 offset:1040
	s_add_i32 s2, s6, 0xc2
	s_ashr_i32 s3, s2, 31
	s_lshl_b64 s[2:3], s[2:3], 13
	s_add_u32 s2, s68, s2
	s_addc_u32 s3, s69, s3
	s_waitcnt lgkmcnt(0)
	v_pk_mul_f32 v[12:13], v[16:17], v[14:15] op_sel_hi:[1,0]
	v_pk_mul_f32 v[16:17], v[18:19], v[14:15] op_sel_hi:[1,0]
	s_add_u32 s2, s2, s0
	v_pk_mul_f32 v[18:19], v[138:139], v[16:17]
	v_pk_mul_f32 v[16:17], v[136:137], v[12:13]
	s_addc_u32 s3, s3, s1
	global_store_dwordx4 v0, v[16:19], s[2:3] nt
	ds_read_b128 v[16:19], v2 offset:2080
	s_add_i32 s2, s6, 0xc3
	s_ashr_i32 s3, s2, 31
	s_lshl_b64 s[2:3], s[2:3], 13
	s_add_u32 s2, s68, s2
	v_mov_b32_e32 v12, v15
	s_addc_u32 s3, s69, s3
	s_waitcnt lgkmcnt(0)
	v_pk_mul_f32 v[16:17], v[16:17], v[12:13] op_sel_hi:[1,0]
	v_pk_mul_f32 v[12:13], v[18:19], v[12:13] op_sel_hi:[1,0]
	s_add_u32 s2, s2, s0
	v_pk_mul_f32 v[14:15], v[138:139], v[12:13]
	v_pk_mul_f32 v[12:13], v[136:137], v[16:17]
	s_addc_u32 s3, s3, s1
	global_store_dwordx4 v0, v[12:15], s[2:3] nt
	ds_read_b128 v[12:15], v2 offset:3120
	s_add_i32 s2, s6, 0xc4
	s_ashr_i32 s3, s2, 31
	s_lshl_b64 s[2:3], s[2:3], 13
	s_add_u32 s2, s68, s2
	s_addc_u32 s3, s69, s3
	s_waitcnt lgkmcnt(0)
	v_pk_mul_f32 v[14:15], v[14:15], v[8:9] op_sel_hi:[1,0]
	v_pk_mul_f32 v[12:13], v[12:13], v[8:9] op_sel_hi:[1,0]
	s_add_u32 s2, s2, s0
	v_pk_mul_f32 v[14:15], v[138:139], v[14:15]
	v_pk_mul_f32 v[12:13], v[136:137], v[12:13]
	s_addc_u32 s3, s3, s1
	global_store_dwordx4 v0, v[12:15], s[2:3] nt
	ds_read_b128 v[12:15], v2 offset:4160
	s_add_i32 s2, s6, 0xc5
	s_ashr_i32 s3, s2, 31
	s_lshl_b64 s[2:3], s[2:3], 13
	s_add_u32 s2, s68, s2
	s_addc_u32 s3, s69, s3
	s_waitcnt lgkmcnt(0)
	v_pk_mul_f32 v[14:15], v[14:15], v[8:9] op_sel:[0,1]
	v_pk_mul_f32 v[8:9], v[12:13], v[8:9] op_sel:[0,1]
	s_add_u32 s2, s2, s0
	v_pk_mul_f32 v[14:15], v[138:139], v[14:15]
	v_pk_mul_f32 v[12:13], v[136:137], v[8:9]
	s_addc_u32 s3, s3, s1
	global_store_dwordx4 v0, v[12:15], s[2:3] nt
	ds_read_b128 v[12:15], v2 offset:5200
	s_add_i32 s2, s6, 0xc6
	s_ashr_i32 s3, s2, 31
	s_lshl_b64 s[2:3], s[2:3], 13
	s_add_u32 s2, s68, s2
	s_addc_u32 s3, s69, s3
	s_waitcnt lgkmcnt(0)
	v_pk_mul_f32 v[8:9], v[12:13], v[10:11] op_sel_hi:[1,0]
	v_pk_mul_f32 v[12:13], v[14:15], v[10:11] op_sel_hi:[1,0]
	s_add_u32 s2, s2, s0
	v_pk_mul_f32 v[14:15], v[138:139], v[12:13]
	v_pk_mul_f32 v[12:13], v[136:137], v[8:9]
	s_addc_u32 s3, s3, s1
	global_store_dwordx4 v0, v[12:15], s[2:3] nt
	ds_read_b128 v[12:15], v2 offset:6240
	s_add_i32 s2, s6, 0xc7
	s_ashr_i32 s3, s2, 31
	s_lshl_b64 s[2:3], s[2:3], 13
	s_add_u32 s2, s68, s2
	v_mov_b32_e32 v2, v11
	s_addc_u32 s3, s69, s3
	s_waitcnt lgkmcnt(0)
	v_pk_mul_f32 v[8:9], v[12:13], v[2:3] op_sel_hi:[1,0]
	v_pk_mul_f32 v[2:3], v[14:15], v[2:3] op_sel_hi:[1,0]
	s_add_u32 s0, s2, s0
	v_pk_mul_f32 v[10:11], v[138:139], v[2:3]
	v_pk_mul_f32 v[8:9], v[136:137], v[8:9]
	s_addc_u32 s1, s3, s1
	global_store_dwordx4 v0, v[8:11], s[0:1] nt
	s_waitcnt lgkmcnt(0)
	s_barrier
